# re-stagger barrier of waves 4-7 moved from after the epilogue to just before the K-loop
# baseline (speedup 1.0000x reference)
; #define PG8_WAIT_V(n) asm volatile("s_waitcnt vmcnt(" #n ")" ::: "memory")
; #define PG8_BAR __builtin_amdgcn_s_barrier()
; #define PG8_STA(bufoff, gbase, ld) PG8_STAGE(bufoff, gbase, RA0 * (unsigned)(ld) + CC0, RA1 * (unsigned)(ld) + CC1)
; #define PG8_STB(bufoff, gbase, ld) PG8_STAGE(bufoff, gbase, RB0 * (unsigned)(ld) + CC0, RB1 * (unsigned)(ld) + CC1)
; __device__ __forceinline__ void epi_rstd(const float* ssq, int row0, int fq, float (&rs)[2][4]) {
;     ...
;         for (int m = 0; m < 4; ++m) { float t = (part[ai][m][0] + part[ai][m][1]) + (part[ai][m][2] + part[ai][m][3]); t += __shfl_xor(t, 16); t += __shfl_xor(t, 32); rs[ai][m] = __builtin_amdgcn_rsqf(t * (1.0f / 1024.0f) + EPS); }
; __device__ __forceinline__ void gemm_phase(LAS unsigned char* lds, const Sched& S, const Epi& E) {
;     ...
;     PG8_WAIT_V(2); PG8_BAR;
;     PG8_STB(PG8_SB(1, 0), cB + kstep, ldb); PG8_STA(PG8_SA(1, 0), cA + kstep, lda); PG8_STB(PG8_SB(1, 1), cB + hB + kstep, ldb);
;     PG8_WAIT_V(6); PG8_BAR; }
;     for (;;) {
;         const bool has_next = S.next(ui + 1, nxt);
;         const char* nA = has_next ? nxt.a : cA; const char* nB = has_next ? nxt.b : cB;
;         const int nlda = has_next ? nxt.lda : lda, nldb = has_next ? nxt.ldb : ldb;
;         const size_t hA = (size_t)HALF * lda * 2;
;         const int nt = cur.nt;
;         const int nt_main = has_next ? nt : nt - 2;
.LBB0_256:
	v_bfe_u32 v19, v17, 4, 2
	v_and_b32_e32 v18, 15, v17
	v_lshlrev_b32_e32 v21, 4, v19
	v_lshlrev_b32_e32 v17, 2, v17
	s_and_b32 s11, s7, 3
	v_lshl_or_b32 v239, s6, 6, v18
	v_lshl_or_b32 v18, v18, 6, v21
	s_lshl_b32 s6, s6, 13
	v_and_b32_e32 v17, 32, v17
	v_bitop3_b32 v240, v18, s6, v17 bitop3:0xde
	s_lshl_b32 s6, s11, 12
	v_bitop3_b32 v241, v18, s6, v17 bitop3:0xde
	v_readlane_b32 s6, v250, 7
	v_readlane_b32 s7, v250, 8
	s_lshl_b64 s[6:7], s[6:7], 2
	s_waitcnt lgkmcnt(0)
	s_add_u32 s4, s4, s6
	s_addc_u32 s5, s5, s7
	s_add_u32 s62, s70, 0x800000
	s_addc_u32 s63, s71, 0
	v_lshl_add_u64 v[2:3], v[2:3], 0, s[52:53]
	s_add_i32 m0, s34, 0x18000
	s_waitcnt vmcnt(2)
	s_barrier
	global_load_lds_dwordx4 v[2:3], off
	v_lshl_add_u64 v[2:3], v[4:5], 0, s[52:53]
	s_add_i32 m0, s34, 0x1a000
	s_add_i32 s90, s34, 0x8000
	global_load_lds_dwordx4 v[2:3], off
	v_lshl_add_u64 v[2:3], v[10:11], 0, s[52:53]
	s_mov_b32 m0, s90
	s_add_i32 s73, s34, 0xa000
	global_load_lds_dwordx4 v[2:3], off
	v_lshl_add_u64 v[2:3], v[12:13], 0, s[52:53]
	s_mov_b32 m0, s73
	v_writelane_b32 v250, s4, 27
	global_load_lds_dwordx4 v[2:3], off
	v_lshl_add_u64 v[2:3], v[6:7], 0, s[52:53]
	s_add_i32 m0, s34, 0x1c000
	v_writelane_b32 v250, s5, 28
	global_load_lds_dwordx4 v[2:3], off
	v_lshl_add_u64 v[2:3], v[8:9], 0, s[52:53]
	s_add_i32 m0, s34, 0x1e000
	s_cmpk_lt_u32 s2, 0x100
	global_load_lds_dwordx4 v[2:3], off
	s_cselect_b64 s[4:5], -1, 0
	s_lshl_b32 s6, s11, 14
	v_writelane_b32 v250, s11, 29
	s_or_b32 s6, s6, 0xfff80000
	v_writelane_b32 v250, s6, 30
	s_lshl_b32 s82, s15, 3
	v_readlane_b32 s6, v250, 21
	v_readlane_b32 s7, v250, 22
	v_readlane_b32 s61, v250, 20
	s_waitcnt vmcnt(6)
	v_add_f32_e32 v66, v66, v67
	v_add_f32_e32 v68, v68, v69
	v_add_f32_e32 v66, v66, v68
	v_add_f32_e32 v70, v70, v71
	v_add_f32_e32 v72, v72, v73
	v_add_f32_e32 v70, v70, v72
	v_add_f32_e32 v74, v74, v75
	v_add_f32_e32 v76, v76, v77
	v_add_f32_e32 v74, v74, v76
	v_add_f32_e32 v78, v78, v79
	v_add_f32_e32 v80, v80, v81
	v_add_f32_e32 v78, v78, v80
	v_add_f32_e32 v66, v66, v70
	v_add_f32_e32 v74, v74, v78
	v_add_f32_e32 v66, v66, v74
	v_fmamk_f32 v66, v66, 0x3a800000, v197
	v_rsq_f32_e32 v66, v66
	v_and_b32_e32 v65, 0xff, v195
	v_lshlrev_b32_e32 v65, 2, v65
	v_add_u32_e32 v65, 0x20800, v65
	ds_write_b32 v65, v66
	v_writelane_b32 v250, s95, 41
	v_and_b32_e32 v0, 1, v0
	v_cndmask_b32_e64 v2, 0, 1, s[6:7]
	s_lshr_b32 s6, s61, 6
	v_readfirstlane_b32 s36, v2
	v_cvt_f32_u32_e32 v2, s82
	v_writelane_b32 v250, s6, 31
	s_sub_i32 s6, 0, s82
	v_lshlrev_b32_e32 v20, 3, v19
	v_rcp_iflag_f32_e32 v2, v2
	v_lshlrev_b32_e32 v198, 16, v19
	v_lshl_or_b32 v242, s11, 5, v20
	s_mov_b32 s2, 0
	v_mul_f32_e32 v2, 0x4f7ffffe, v2
	v_cvt_u32_f32_e32 v2, v2
	v_cmp_eq_u32_e64 s[40:41], 0, v19
	v_or_b32_e32 v200, 0x4000, v198
	v_or_b32_e32 v202, 0x8000, v198
	v_readfirstlane_b32 s7, v2
	s_mul_i32 s6, s6, s7
	s_mul_hi_u32 s6, s7, s6
	s_add_i32 s6, s7, s6
	v_writelane_b32 v250, s6, 32
	v_lshlrev_b32_e32 v2, 1, v14
	v_lshl_add_u32 v206, v0, 6, v2
	v_and_b32_e32 v0, 1, v15
	v_lshlrev_b32_e32 v2, 1, v16
	v_readlane_b32 s6, v250, 12
	v_or_b32_e32 v204, 0xc000, v198
	s_mov_b32 s17, s31
	v_lshl_add_u32 v208, v0, 6, v2
	v_readlane_b32 s83, v250, 13
	s_mov_b32 s20, s6
	s_mov_b32 s11, s61
	s_mov_b64 s[12:13], s[8:9]
	s_mov_b64 s[6:7], s[96:97]
	s_waitcnt lgkmcnt(0)
	s_barrier
	s_mov_b32 s21, 0
	s_nop 0
	v_writelane_b32 v250, s21, 42
	s_branch .LBB0_259

; #define PG8_LDA(dst, b, h) do { _Pragma("unroll") for (int m = 0; m < 4; ++m) _Pragma("unroll") for (int k = 0; k < 2; ++k) dst[m][k] = *(const LAS bf16x8*)(lds + PG8_SA(b, h) + aoff + m * 2048 + k * 1024); } while (0)
; #define PG8_LDB(dst, b, h) do { _Pragma("unroll") for (int n = 0; n < 2; ++n) _Pragma("unroll") for (int k = 0; k < 2; ++k) dst[n][k] = *(const LAS bf16x8*)(lds + PG8_SB(b, h) + boff + n * 2048 + k * 1024); } while (0)
; #define PG8_BAR __builtin_amdgcn_s_barrier()
; #define PG8_SCHED __builtin_amdgcn_sched_barrier(0)
; #define PG8_STA(bufoff, gbase, ld) PG8_STAGE(bufoff, gbase, RA0 * (unsigned)(ld) + CC0, RA1 * (unsigned)(ld) + CC1)
; __device__ __forceinline__ void gemm_phase(LAS unsigned char* lds, const Sched& S, const Epi& E) {
;     ...
;         const bool has_next = S.next(ui + 1, nxt);
;         const char* nA = has_next ? nxt.a : cA; const char* nB = has_next ? nxt.b : cB;
;         const int nlda = has_next ? nxt.lda : lda, nldb = has_next ? nxt.ldb : ldb;
;         const size_t hA = (size_t)HALF * lda * 2;
;         const int nt = cur.nt;
;         const int nt_main = has_next ? nt : nt - 2;
;         for (int t = 0; t < nt_main; t += 2) {
;             const bool last = (t == nt - 2);
;             const char* a1 = cA + (size_t)(t + 1) * kstep;
;             const char* a2 = last ? nA : cA + (size_t)(t + 2) * kstep; const char* b2 = last ? nB : cB + (size_t)(t + 2) * kstep;
;             const char* a3 = a2 + kstep; const char* b3 = b2 + kstep;
;             const int xlda = last ? nlda : lda, xldb = last ? nldb : ldb;
;             const size_t xhA = (size_t)HALF * xlda * 2, xhB = (size_t)HALF * xldb * 2;
;             PG8_LDB(B0, 0, 0); PG8_LDB(B1, 0, 1); PG8_SCHED; PG8_LDA(At, 0, 0); PG8_STA(PG8_SA(1, 1), a1 + hA, lda);
;     ...
; #pragma unroll
;         for (int a = 0; a < 2; ++a)
; #pragma unroll
;             for (int b = 0; b < 2; ++b)
; #pragma unroll
;                 for (int m = 0; m < 4; ++m)
; #pragma unroll
;                     for (int n = 0; n < 2; ++n) acc[a][b][m][n] = (f32x4){0.f, 0.f, 0.f, 0.f};
;         cur = nxt; cA = nA; cB = nB; lda = nlda; ldb = nldb; ++ui;
;         if (wr == 1) PG8_BAR;
.LBB0_261:
	s_mov_b32 s21, s31
	s_lshl_b64 s[66:67], s[20:21], 8
	s_add_i32 s21, s60, -2
	s_and_b64 s[26:27], s[42:43], exec
	s_cselect_b32 s68, s60, s21
	s_cmp_lt_i32 s68, 1
	s_cbranch_scc1 .LBB0_274
	s_add_u32 vcc_lo, s96, 0x80
	s_addc_u32 vcc_hi, s97, 0
	s_add_u32 s2, s8, 0x100
	s_addc_u32 s72, s9, 0
	v_mad_u64_u32 v[2:3], s[8:9], s20, v235, v[206:207]
	v_mov_b32_e32 v3, v1
	s_waitcnt lgkmcnt(0)
	v_lshl_add_u64 v[130:131], s[66:67], 0, v[2:3]
	v_mad_u64_u32 v[2:3], s[8:9], s20, v236, v[208:209]
	v_mov_b32_e32 v3, v1
	v_lshl_add_u64 v[132:133], s[66:67], 0, v[2:3]
	v_mov_b32_e32 v2, 0
	s_mov_b32 s3, s92
	s_mov_b32 s8, 0
	v_mov_b32_e32 v3, v2
	v_mov_b32_e32 v4, v2
	v_mov_b32_e32 v5, v2
	v_mov_b32_e32 v6, v2
	v_mov_b32_e32 v7, v2
	v_mov_b32_e32 v8, v2
	v_mov_b32_e32 v9, v2
	v_mov_b32_e32 v18, v2
	v_mov_b32_e32 v19, v2
	v_mov_b32_e32 v20, v2
	v_mov_b32_e32 v21, v2
	v_mov_b32_e32 v22, v2
	v_mov_b32_e32 v23, v2
	v_mov_b32_e32 v24, v2
	v_mov_b32_e32 v25, v2
	v_mov_b32_e32 v34, v2
	v_mov_b32_e32 v35, v2
	v_mov_b32_e32 v36, v2
	v_mov_b32_e32 v37, v2
	v_mov_b32_e32 v38, v2
	v_mov_b32_e32 v39, v2
	v_mov_b32_e32 v40, v2
	v_mov_b32_e32 v41, v2
	v_mov_b32_e32 v50, v2
	v_mov_b32_e32 v51, v2
	v_mov_b32_e32 v52, v2
	v_mov_b32_e32 v53, v2
	v_mov_b32_e32 v54, v2
	v_mov_b32_e32 v55, v2
	v_mov_b32_e32 v56, v2
	v_mov_b32_e32 v57, v2
	v_mov_b32_e32 v10, v2
	v_mov_b32_e32 v11, v2
	v_mov_b32_e32 v12, v2
	v_mov_b32_e32 v13, v2
	v_mov_b32_e32 v14, v2
	v_mov_b32_e32 v15, v2
	v_mov_b32_e32 v16, v2
	v_mov_b32_e32 v17, v2
	v_mov_b32_e32 v26, v2
	v_mov_b32_e32 v27, v2
	v_mov_b32_e32 v28, v2
	v_mov_b32_e32 v29, v2
	v_mov_b32_e32 v30, v2
	v_mov_b32_e32 v31, v2
	v_mov_b32_e32 v32, v2
	v_mov_b32_e32 v33, v2
	v_mov_b32_e32 v42, v2
	v_mov_b32_e32 v43, v2
	v_mov_b32_e32 v44, v2
	v_mov_b32_e32 v45, v2
	v_mov_b32_e32 v46, v2
	v_mov_b32_e32 v47, v2
	v_mov_b32_e32 v48, v2
	v_mov_b32_e32 v49, v2
	v_mov_b32_e32 v58, v2
	v_mov_b32_e32 v59, v2
	v_mov_b32_e32 v60, v2
	v_mov_b32_e32 v61, v2
	v_mov_b32_e32 v62, v2
	v_mov_b32_e32 v63, v2
	v_mov_b32_e32 v64, v2
	v_mov_b32_e32 v65, v2
	v_mov_b32_e32 v66, v2
	v_mov_b32_e32 v67, v2
	v_mov_b32_e32 v68, v2
	v_mov_b32_e32 v69, v2
	v_mov_b32_e32 v70, v2
	v_mov_b32_e32 v71, v2
	v_mov_b32_e32 v72, v2
	v_mov_b32_e32 v73, v2
	v_mov_b32_e32 v78, v2
	v_mov_b32_e32 v79, v2
	v_mov_b32_e32 v80, v2
	v_mov_b32_e32 v81, v2
	v_mov_b32_e32 v86, v2
	v_mov_b32_e32 v87, v2
	v_mov_b32_e32 v88, v2
	v_mov_b32_e32 v89, v2
	v_mov_b32_e32 v94, v2
	v_mov_b32_e32 v95, v2
	v_mov_b32_e32 v96, v2
	v_mov_b32_e32 v97, v2
	v_mov_b32_e32 v102, v2
	v_mov_b32_e32 v103, v2
	v_mov_b32_e32 v104, v2
	v_mov_b32_e32 v105, v2
	v_mov_b32_e32 v114, v2
	v_mov_b32_e32 v115, v2
	v_mov_b32_e32 v116, v2
	v_mov_b32_e32 v117, v2
	v_mov_b32_e32 v118, v2
	v_mov_b32_e32 v119, v2
	v_mov_b32_e32 v120, v2
	v_mov_b32_e32 v121, v2
	v_mov_b32_e32 v74, v2
	v_mov_b32_e32 v75, v2
	v_mov_b32_e32 v76, v2
	v_mov_b32_e32 v77, v2
	v_mov_b32_e32 v82, v2
	v_mov_b32_e32 v83, v2
	v_mov_b32_e32 v84, v2
	v_mov_b32_e32 v85, v2
	v_mov_b32_e32 v90, v2
	v_mov_b32_e32 v91, v2
	v_mov_b32_e32 v92, v2
	v_mov_b32_e32 v93, v2
	v_mov_b32_e32 v98, v2
	v_mov_b32_e32 v99, v2
	v_mov_b32_e32 v100, v2
	v_mov_b32_e32 v101, v2
	v_mov_b32_e32 v106, v2
	v_mov_b32_e32 v107, v2
	v_mov_b32_e32 v108, v2
	v_mov_b32_e32 v109, v2
	v_mov_b32_e32 v110, v2
	v_mov_b32_e32 v111, v2
	v_mov_b32_e32 v112, v2
	v_mov_b32_e32 v113, v2
	v_mov_b32_e32 v122, v2
	v_mov_b32_e32 v123, v2
	v_mov_b32_e32 v124, v2
	v_mov_b32_e32 v125, v2
	v_mov_b32_e32 v126, v2
	v_mov_b32_e32 v127, v2
	v_mov_b32_e32 v128, v2
	v_mov_b32_e32 v129, v2
	v_readlane_b32 s24, v250, 42
	s_nop 0
	s_cmp_eq_u32 s24, 0
	s_cbranch_scc1 .Lmy_nostagger
	s_barrier
.Lmy_nostagger:
.LBB0_263:
	s_add_i32 s24, s8, 2
	s_add_u32 s26, vcc_lo, 0x80
	s_addc_u32 s9, vcc_hi, 0
	s_add_i32 s37, 0, 0x10000
	s_cmp_eq_u32 s21, s8
	s_cselect_b32 s9, s7, s9
	s_cselect_b32 s8, s6, s26
	s_cselect_b32 s92, s11, s61
	s_cselect_b32 s30, s22, s20
	v_add_u32_e32 v0, s37, v241
	s_cselect_b32 s29, s13, s72
	s_cselect_b32 s28, s12, s2
	s_add_i32 s57, 0, 0x14000
	ds_read_b128 v[134:137], v0
	ds_read_b128 v[138:141], v0 offset:1024
	ds_read_b128 v[142:145], v0 offset:2048
	ds_read_b128 v[146:149], v0 offset:3072
	v_add_u32_e32 v0, s57, v241
	ds_read_b128 v[150:153], v0
	ds_read_b128 v[154:157], v0 offset:1024
	ds_read_b128 v[158:161], v0 offset:2048
	ds_read_b128 v[162:165], v0 offset:3072
	s_mov_b32 s93, s31
	s_lshl_b64 s[26:27], s[30:31], 8
	v_add_u32_e32 v0, 0, v240
	v_lshl_add_u64 v[214:215], vcc, 0, v[130:131]
	s_add_i32 m0, s34, 0xc000
	ds_read_b128 v[166:169], v0
	ds_read_b128 v[170:173], v0 offset:1024
	ds_read_b128 v[174:177], v0 offset:2048
	ds_read_b128 v[178:181], v0 offset:3072
	ds_read_b128 v[182:185], v0 offset:4096
	ds_read_b128 v[186:189], v0 offset:5120
	ds_read_b128 v[190:193], v0 offset:6144
	ds_read_b128 v[210:213], v0 offset:7168
	global_load_lds_dwordx4 v[214:215], off
	v_lshl_add_u64 v[214:215], vcc, 0, v[132:133]
	s_add_i32 m0, s34, 0xe000
	s_nop 0
	global_load_lds_dwordx4 v[214:215], off
	s_waitcnt vmcnt(8)
	s_waitcnt lgkmcnt(0)
	s_barrier
; #define PG8_LDA(dst, b, h) do { _Pragma("unroll") for (int m = 0; m < 4; ++m) _Pragma("unroll") for (int k = 0; k < 2; ++k) dst[m][k] = *(const LAS bf16x8*)(lds + PG8_SA(b, h) + aoff + m * 2048 + k * 1024); } while (0)
; #define PG8_LDB(dst, b, h) do { _Pragma("unroll") for (int n = 0; n < 2; ++n) _Pragma("unroll") for (int k = 0; k < 2; ++k) dst[n][k] = *(const LAS bf16x8*)(lds + PG8_SB(b, h) + boff + n * 2048 + k * 1024); } while (0)
; #define PG8_MMA(ai, bj, At, Bt) do { __builtin_amdgcn_s_setprio(1); _Pragma("unroll") for (int m = 0; m < 4; ++m) _Pragma("unroll") for (int n = 0; n < 2; ++n) _Pragma("unroll") for (int k = 0; k < 2; ++k) \
;         acc[ai][bj][m][n] = __builtin_amdgcn_mfma_f32_16x16x32_bf16(Bt[n][k], At[m][k], acc[ai][bj][m][n], 0, 0, 0); __builtin_amdgcn_s_setprio(0); } while (0)
; #define PG8_WAIT_V(n) asm volatile("s_waitcnt vmcnt(" #n ")" ::: "memory")
; #define PG8_WAIT_L(n) asm volatile("s_waitcnt lgkmcnt(" #n ")" ::: "memory")
; #define PG8_BAR __builtin_amdgcn_s_barrier()
; #define PG8_SCHED __builtin_amdgcn_sched_barrier(0)
; #define PG8_STA(bufoff, gbase, ld) PG8_STAGE(bufoff, gbase, RA0 * (unsigned)(ld) + CC0, RA1 * (unsigned)(ld) + CC1)
; #define PG8_STB(bufoff, gbase, ld) PG8_STAGE(bufoff, gbase, RB0 * (unsigned)(ld) + CC0, RB1 * (unsigned)(ld) + CC1)
; __device__ __forceinline__ void gemm_phase(LAS unsigned char* lds, const Sched& S, const Epi& E) {
;     ...
;             PG8_LDB(B0, 0, 0); PG8_LDB(B1, 0, 1); PG8_SCHED; PG8_LDA(At, 0, 0); PG8_STA(PG8_SA(1, 1), a1 + hA, lda);
;             PG8_WAIT_V(8); PG8_WAIT_L(0); PG8_BAR; PG8_MMA(0, 0, At, B0); PG8_MMA(0, 1, At, B1); PG8_BAR; PG8_SCHED;
;             PG8_LDA(At, 0, 1); PG8_STB(PG8_SB(0, 0), b2, xldb); PG8_STB(PG8_SB(0, 1), b2 + xhB, xldb); PG8_STA(PG8_SA(0, 0), a2, xlda);
;             PG8_WAIT_V(8); PG8_WAIT_L(0); PG8_BAR; PG8_MMA(1, 0, At, B0); PG8_MMA(1, 1, At, B1); PG8_BAR; PG8_SCHED;
	s_setprio 1
	s_waitcnt lgkmcnt(0)
	v_mfma_f32_16x16x32_bf16 v[126:129], v[134:137], v[166:169], v[126:129]
	v_mfma_f32_16x16x32_bf16 v[122:125], v[142:145], v[166:169], v[122:125]
	v_mfma_f32_16x16x32_bf16 v[110:113], v[134:137], v[174:177], v[110:113]
	v_mfma_f32_16x16x32_bf16 v[106:109], v[142:145], v[174:177], v[106:109]
	v_mfma_f32_16x16x32_bf16 v[98:101], v[134:137], v[182:185], v[98:101]
	v_mfma_f32_16x16x32_bf16 v[90:93], v[142:145], v[182:185], v[90:93]
	v_mfma_f32_16x16x32_bf16 v[82:85], v[134:137], v[190:193], v[82:85]
	v_mfma_f32_16x16x32_bf16 v[74:77], v[142:145], v[190:193], v[74:77]
	v_mfma_f32_16x16x32_bf16 v[126:129], v[138:141], v[170:173], v[126:129]
	v_mfma_f32_16x16x32_bf16 v[122:125], v[146:149], v[170:173], v[122:125]
	v_mfma_f32_16x16x32_bf16 v[110:113], v[138:141], v[178:181], v[110:113]
	v_mfma_f32_16x16x32_bf16 v[106:109], v[146:149], v[178:181], v[106:109]
	v_mfma_f32_16x16x32_bf16 v[98:101], v[138:141], v[186:189], v[98:101]
	v_mfma_f32_16x16x32_bf16 v[90:93], v[146:149], v[186:189], v[90:93]
	v_mfma_f32_16x16x32_bf16 v[82:85], v[138:141], v[210:213], v[82:85]
	v_mfma_f32_16x16x32_bf16 v[74:77], v[146:149], v[210:213], v[74:77]
	s_setprio 0
	s_setprio 1
	v_mfma_f32_16x16x32_bf16 v[118:121], v[150:153], v[166:169], v[118:121]
	v_mfma_f32_16x16x32_bf16 v[114:117], v[158:161], v[166:169], v[114:117]
	v_mfma_f32_16x16x32_bf16 v[102:105], v[150:153], v[174:177], v[102:105]
	v_mfma_f32_16x16x32_bf16 v[94:97], v[158:161], v[174:177], v[94:97]
	v_mfma_f32_16x16x32_bf16 v[86:89], v[150:153], v[182:185], v[86:89]
	v_mfma_f32_16x16x32_bf16 v[78:81], v[158:161], v[182:185], v[78:81]
	v_mfma_f32_16x16x32_bf16 v[70:73], v[150:153], v[190:193], v[70:73]
	v_mfma_f32_16x16x32_bf16 v[66:69], v[158:161], v[190:193], v[66:69]
	v_mfma_f32_16x16x32_bf16 v[118:121], v[154:157], v[170:173], v[118:121]
	v_mfma_f32_16x16x32_bf16 v[114:117], v[162:165], v[170:173], v[114:117]
	v_mfma_f32_16x16x32_bf16 v[102:105], v[154:157], v[178:181], v[102:105]
	v_mfma_f32_16x16x32_bf16 v[94:97], v[162:165], v[178:181], v[94:97]
	v_mfma_f32_16x16x32_bf16 v[86:89], v[154:157], v[186:189], v[86:89]
	v_mfma_f32_16x16x32_bf16 v[78:81], v[162:165], v[186:189], v[78:81]
	v_mfma_f32_16x16x32_bf16 v[70:73], v[154:157], v[210:213], v[70:73]
	v_mfma_f32_16x16x32_bf16 v[66:69], v[162:165], v[210:213], v[66:69]
	s_setprio 0
	s_barrier
	s_add_i32 s37, s37, s25
	v_mad_u64_u32 v[214:215], s[80:81], s92, v237, v[194:195]
	s_mov_b32 m0, s37
	ds_read_b128 v[166:169], v0 offset:16384
	ds_read_b128 v[170:173], v0 offset:17408
	ds_read_b128 v[174:177], v0 offset:18432
	ds_read_b128 v[178:181], v0 offset:19456
	ds_read_b128 v[182:185], v0 offset:20480
	ds_read_b128 v[186:189], v0 offset:21504
	ds_read_b128 v[190:193], v0 offset:22528
	ds_read_b128 v[210:213], v0 offset:23552
	s_lshl_b64 s[74:75], s[92:93], 8
	global_load_lds_dwordx4 v214, s[28:29]
	s_add_i32 m0, s37, 0x2000
	s_add_u32 s74, s28, s74
	v_mad_u64_u32 v[216:217], s[80:81], s92, v238, v[196:197]
	s_addc_u32 s75, s29, s75
	s_add_i32 s37, s57, s25
	global_load_lds_dwordx4 v216, s[28:29]
	s_mov_b32 m0, s37
	v_mad_u64_u32 v[218:219], s[80:81], s30, v235, v[194:195]
	global_load_lds_dwordx4 v214, s[74:75]
	s_add_i32 m0, s37, 0x2000
	v_mad_u64_u32 v[220:221], s[80:81], s30, v236, v[196:197]
	global_load_lds_dwordx4 v216, s[74:75]
	s_mov_b32 m0, s34
	v_mov_b32_e32 v215, v1
	global_load_lds_dwordx4 v218, s[8:9]
	s_mov_b32 m0, s35
	v_mov_b32_e32 v217, v1
	global_load_lds_dwordx4 v220, s[8:9]
	v_mov_b32_e32 v219, v1
	v_mov_b32_e32 v221, v1
	v_lshl_add_u64 v[222:223], s[28:29], 0, v[214:215]
	v_lshl_add_u64 v[224:225], s[28:29], 0, v[216:217]
	v_lshl_add_u64 v[214:215], s[74:75], 0, v[214:215]
	v_lshl_add_u64 v[216:217], s[74:75], 0, v[216:217]
	v_lshl_add_u64 v[226:227], s[8:9], 0, v[218:219]
	v_lshl_add_u64 v[228:229], s[8:9], 0, v[220:221]
	s_waitcnt vmcnt(8)
	s_waitcnt lgkmcnt(0)
	s_barrier
	s_setprio 1
	s_waitcnt lgkmcnt(0)
	v_mfma_f32_16x16x32_bf16 v[62:65], v[134:137], v[166:169], v[62:65]
	v_mfma_f32_16x16x32_bf16 v[58:61], v[142:145], v[166:169], v[58:61]
	v_mfma_f32_16x16x32_bf16 v[46:49], v[134:137], v[174:177], v[46:49]
	v_mfma_f32_16x16x32_bf16 v[42:45], v[142:145], v[174:177], v[42:45]
	v_mfma_f32_16x16x32_bf16 v[30:33], v[134:137], v[182:185], v[30:33]
	v_mfma_f32_16x16x32_bf16 v[26:29], v[142:145], v[182:185], v[26:29]
	v_mfma_f32_16x16x32_bf16 v[14:17], v[134:137], v[190:193], v[14:17]
	v_mfma_f32_16x16x32_bf16 v[10:13], v[142:145], v[190:193], v[10:13]
	v_mfma_f32_16x16x32_bf16 v[62:65], v[138:141], v[170:173], v[62:65]
	v_mfma_f32_16x16x32_bf16 v[58:61], v[146:149], v[170:173], v[58:61]
	v_mfma_f32_16x16x32_bf16 v[46:49], v[138:141], v[178:181], v[46:49]
	v_mfma_f32_16x16x32_bf16 v[42:45], v[146:149], v[178:181], v[42:45]
	v_mfma_f32_16x16x32_bf16 v[30:33], v[138:141], v[186:189], v[30:33]
	v_mfma_f32_16x16x32_bf16 v[26:29], v[146:149], v[186:189], v[26:29]
	v_mfma_f32_16x16x32_bf16 v[14:17], v[138:141], v[210:213], v[14:17]
	v_mfma_f32_16x16x32_bf16 v[10:13], v[146:149], v[210:213], v[10:13]
	s_setprio 0
	s_setprio 1
	v_mfma_f32_16x16x32_bf16 v[54:57], v[150:153], v[166:169], v[54:57]
	v_mfma_f32_16x16x32_bf16 v[50:53], v[158:161], v[166:169], v[50:53]
	v_mfma_f32_16x16x32_bf16 v[38:41], v[150:153], v[174:177], v[38:41]
	v_mfma_f32_16x16x32_bf16 v[34:37], v[158:161], v[174:177], v[34:37]
	v_mfma_f32_16x16x32_bf16 v[22:25], v[150:153], v[182:185], v[22:25]
	v_mfma_f32_16x16x32_bf16 v[18:21], v[158:161], v[182:185], v[18:21]
	v_mfma_f32_16x16x32_bf16 v[6:9], v[150:153], v[190:193], v[6:9]
	v_mfma_f32_16x16x32_bf16 v[2:5], v[158:161], v[190:193], v[2:5]
	v_mfma_f32_16x16x32_bf16 v[54:57], v[154:157], v[170:173], v[54:57]
	v_mfma_f32_16x16x32_bf16 v[50:53], v[162:165], v[170:173], v[50:53]
	v_mfma_f32_16x16x32_bf16 v[38:41], v[154:157], v[178:181], v[38:41]
	v_mfma_f32_16x16x32_bf16 v[34:37], v[162:165], v[178:181], v[34:37]
	v_mfma_f32_16x16x32_bf16 v[22:25], v[154:157], v[186:189], v[22:25]
	v_mfma_f32_16x16x32_bf16 v[18:21], v[162:165], v[186:189], v[18:21]
	v_mfma_f32_16x16x32_bf16 v[6:9], v[154:157], v[210:213], v[6:9]
	v_mfma_f32_16x16x32_bf16 v[2:5], v[162:165], v[210:213], v[2:5]
	s_setprio 0
	s_barrier
; #define PG8_LDA(dst, b, h) do { _Pragma("unroll") for (int m = 0; m < 4; ++m) _Pragma("unroll") for (int k = 0; k < 2; ++k) dst[m][k] = *(const LAS bf16x8*)(lds + PG8_SA(b, h) + aoff + m * 2048 + k * 1024); } while (0)
; #define PG8_LDB(dst, b, h) do { _Pragma("unroll") for (int n = 0; n < 2; ++n) _Pragma("unroll") for (int k = 0; k < 2; ++k) dst[n][k] = *(const LAS bf16x8*)(lds + PG8_SB(b, h) + boff + n * 2048 + k * 1024); } while (0)
; #define PG8_MMA(ai, bj, At, Bt) do { __builtin_amdgcn_s_setprio(1); _Pragma("unroll") for (int m = 0; m < 4; ++m) _Pragma("unroll") for (int n = 0; n < 2; ++n) _Pragma("unroll") for (int k = 0; k < 2; ++k) \
;         acc[ai][bj][m][n] = __builtin_amdgcn_mfma_f32_16x16x32_bf16(Bt[n][k], At[m][k], acc[ai][bj][m][n], 0, 0, 0); __builtin_amdgcn_s_setprio(0); } while (0)
; #define PG8_WAIT_V(n) asm volatile("s_waitcnt vmcnt(" #n ")" ::: "memory")
; #define PG8_WAIT_L(n) asm volatile("s_waitcnt lgkmcnt(" #n ")" ::: "memory")
; #define PG8_BAR __builtin_amdgcn_s_barrier()
; #define PG8_SCHED __builtin_amdgcn_sched_barrier(0)
; #define PG8_STA(bufoff, gbase, ld) PG8_STAGE(bufoff, gbase, RA0 * (unsigned)(ld) + CC0, RA1 * (unsigned)(ld) + CC1)
; __device__ __forceinline__ void gemm_phase(LAS unsigned char* lds, const Sched& S, const Epi& E) {
;     ...
;             PG8_LDB(B0, 1, 0); PG8_LDB(B1, 1, 1); PG8_SCHED; PG8_LDA(At, 1, 0); PG8_STA(PG8_SA(0, 1), a2 + xhA, xlda);
;             PG8_WAIT_V(8); PG8_WAIT_L(0); PG8_BAR; PG8_MMA(0, 0, At, B0); PG8_MMA(0, 1, At, B1); PG8_BAR; PG8_SCHED;
	s_add_i32 s28, 0, 0x18000
	s_add_i32 s29, 0, 0x1c000
	v_add_u32_e32 v146, s28, v241
	v_add_u32_e32 v162, s29, v241
	ds_read_b128 v[134:137], v146
	ds_read_b128 v[138:141], v146 offset:1024
	ds_read_b128 v[142:145], v146 offset:2048
	ds_read_b128 v[146:149], v146 offset:3072
	ds_read_b128 v[150:153], v162
	ds_read_b128 v[154:157], v162 offset:1024
	ds_read_b128 v[158:161], v162 offset:2048
	ds_read_b128 v[162:165], v162 offset:3072
	s_add_u32 s8, s8, s26
	s_addc_u32 s9, s9, s27
	s_mov_b32 m0, s39
	ds_read_b128 v[166:169], v0 offset:32768
	ds_read_b128 v[170:173], v0 offset:33792
	ds_read_b128 v[174:177], v0 offset:34816
	ds_read_b128 v[178:181], v0 offset:35840
	ds_read_b128 v[182:185], v0 offset:36864
	ds_read_b128 v[186:189], v0 offset:37888
	ds_read_b128 v[190:193], v0 offset:38912
	ds_read_b128 v[210:213], v0 offset:39936
	global_load_lds_dwordx4 v218, s[8:9]
	s_mov_b32 m0, s91
	s_nop 0
	global_load_lds_dwordx4 v220, s[8:9]
	s_waitcnt vmcnt(8)
	s_waitcnt lgkmcnt(0)
	s_barrier
	s_setprio 1
	s_waitcnt lgkmcnt(0)
	v_mfma_f32_16x16x32_bf16 v[126:129], v[134:137], v[166:169], v[126:129]
	v_mfma_f32_16x16x32_bf16 v[122:125], v[142:145], v[166:169], v[122:125]
	v_mfma_f32_16x16x32_bf16 v[110:113], v[134:137], v[174:177], v[110:113]
	v_mfma_f32_16x16x32_bf16 v[106:109], v[142:145], v[174:177], v[106:109]
	v_mfma_f32_16x16x32_bf16 v[98:101], v[134:137], v[182:185], v[98:101]
	v_mfma_f32_16x16x32_bf16 v[90:93], v[142:145], v[182:185], v[90:93]
	v_mfma_f32_16x16x32_bf16 v[82:85], v[134:137], v[190:193], v[82:85]
	v_mfma_f32_16x16x32_bf16 v[74:77], v[142:145], v[190:193], v[74:77]
	v_mfma_f32_16x16x32_bf16 v[126:129], v[138:141], v[170:173], v[126:129]
	v_mfma_f32_16x16x32_bf16 v[122:125], v[146:149], v[170:173], v[122:125]
	v_mfma_f32_16x16x32_bf16 v[110:113], v[138:141], v[178:181], v[110:113]
	v_mfma_f32_16x16x32_bf16 v[106:109], v[146:149], v[178:181], v[106:109]
	v_mfma_f32_16x16x32_bf16 v[98:101], v[138:141], v[186:189], v[98:101]
	v_mfma_f32_16x16x32_bf16 v[90:93], v[146:149], v[186:189], v[90:93]
	v_mfma_f32_16x16x32_bf16 v[82:85], v[138:141], v[210:213], v[82:85]
	v_mfma_f32_16x16x32_bf16 v[74:77], v[146:149], v[210:213], v[74:77]
	s_setprio 0
	s_setprio 1
	v_mfma_f32_16x16x32_bf16 v[118:121], v[150:153], v[166:169], v[118:121]
	v_mfma_f32_16x16x32_bf16 v[114:117], v[158:161], v[166:169], v[114:117]
	v_mfma_f32_16x16x32_bf16 v[102:105], v[150:153], v[174:177], v[102:105]
	v_mfma_f32_16x16x32_bf16 v[94:97], v[158:161], v[174:177], v[94:97]
	v_mfma_f32_16x16x32_bf16 v[86:89], v[150:153], v[182:185], v[86:89]
	v_mfma_f32_16x16x32_bf16 v[78:81], v[158:161], v[182:185], v[78:81]
	v_mfma_f32_16x16x32_bf16 v[70:73], v[150:153], v[190:193], v[70:73]
	v_mfma_f32_16x16x32_bf16 v[66:69], v[158:161], v[190:193], v[66:69]
	v_mfma_f32_16x16x32_bf16 v[118:121], v[154:157], v[170:173], v[118:121]
	v_mfma_f32_16x16x32_bf16 v[114:117], v[162:165], v[170:173], v[114:117]
	v_mfma_f32_16x16x32_bf16 v[102:105], v[154:157], v[178:181], v[102:105]
	v_mfma_f32_16x16x32_bf16 v[94:97], v[162:165], v[178:181], v[94:97]
	v_mfma_f32_16x16x32_bf16 v[86:89], v[154:157], v[186:189], v[86:89]
	v_mfma_f32_16x16x32_bf16 v[78:81], v[162:165], v[186:189], v[78:81]
	v_mfma_f32_16x16x32_bf16 v[70:73], v[154:157], v[210:213], v[70:73]
	v_mfma_f32_16x16x32_bf16 v[66:69], v[162:165], v[210:213], v[66:69]
	s_setprio 0
	s_barrier
; #define PG8_LDA(dst, b, h) do { _Pragma("unroll") for (int m = 0; m < 4; ++m) _Pragma("unroll") for (int k = 0; k < 2; ++k) dst[m][k] = *(const LAS bf16x8*)(lds + PG8_SA(b, h) + aoff + m * 2048 + k * 1024); } while (0)
; #define PG8_MMA(ai, bj, At, Bt) do { __builtin_amdgcn_s_setprio(1); _Pragma("unroll") for (int m = 0; m < 4; ++m) _Pragma("unroll") for (int n = 0; n < 2; ++n) _Pragma("unroll") for (int k = 0; k < 2; ++k) \
;         acc[ai][bj][m][n] = __builtin_amdgcn_mfma_f32_16x16x32_bf16(Bt[n][k], At[m][k], acc[ai][bj][m][n], 0, 0, 0); __builtin_amdgcn_s_setprio(0); } while (0)
; #define PG8_WAIT_V(n) asm volatile("s_waitcnt vmcnt(" #n ")" ::: "memory")
; #define PG8_WAIT_L(n) asm volatile("s_waitcnt lgkmcnt(" #n ")" ::: "memory")
; #define PG8_BAR __builtin_amdgcn_s_barrier()
; #define PG8_SCHED __builtin_amdgcn_sched_barrier(0)
; #define PG8_STA(bufoff, gbase, ld) PG8_STAGE(bufoff, gbase, RA0 * (unsigned)(ld) + CC0, RA1 * (unsigned)(ld) + CC1)
; #define PG8_STB(bufoff, gbase, ld) PG8_STAGE(bufoff, gbase, RB0 * (unsigned)(ld) + CC0, RB1 * (unsigned)(ld) + CC1)
; __device__ __forceinline__ void gemm_phase(LAS unsigned char* lds, const Sched& S, const Epi& E) {
;     ...
;             PG8_LDA(At, 1, 1); PG8_STB(PG8_SB(1, 0), b3, xldb); PG8_STB(PG8_SB(1, 1), b3 + xhB, xldb); PG8_STA(PG8_SA(1, 0), a3, xlda);
;             PG8_WAIT_V(8); PG8_WAIT_L(0); PG8_BAR; PG8_MMA(1, 0, At, B0); PG8_MMA(1, 1, At, B1); PG8_BAR; PG8_SCHED;
;         }
;         if (!has_next) {
	s_add_i32 s8, s28, s25
	v_lshl_add_u64 v[218:219], v[222:223], 0, s[52:53]
	s_mov_b32 m0, s8
	ds_read_b128 v[166:169], v0 offset:49152
	ds_read_b128 v[170:173], v0 offset:50176
	ds_read_b128 v[174:177], v0 offset:51200
	ds_read_b128 v[178:181], v0 offset:52224
	ds_read_b128 v[182:185], v0 offset:53248
	ds_read_b128 v[186:189], v0 offset:54272
	ds_read_b128 v[190:193], v0 offset:55296
	ds_read_b128 v[210:213], v0 offset:56320
	global_load_lds_dwordx4 v[218:219], off
	v_lshl_add_u64 v[218:219], v[224:225], 0, s[52:53]
	s_add_i32 m0, s8, 0x2000
	s_add_i32 s8, s29, s25
	global_load_lds_dwordx4 v[218:219], off
	v_lshl_add_u64 v[214:215], v[214:215], 0, s[52:53]
	s_mov_b32 m0, s8
	s_nop 0
	global_load_lds_dwordx4 v[214:215], off
	v_lshl_add_u64 v[214:215], v[216:217], 0, s[52:53]
	s_add_i32 m0, s8, 0x2000
	s_nop 0
	global_load_lds_dwordx4 v[214:215], off
	v_lshl_add_u64 v[214:215], v[226:227], 0, s[52:53]
	s_mov_b32 m0, s90
	s_nop 0
	global_load_lds_dwordx4 v[214:215], off
	v_lshl_add_u64 v[214:215], v[228:229], 0, s[52:53]
	s_mov_b32 m0, s73
	s_nop 0
	global_load_lds_dwordx4 v[214:215], off
	s_waitcnt vmcnt(8)
	s_waitcnt lgkmcnt(0)
	s_barrier
	s_setprio 1
	s_waitcnt lgkmcnt(0)
	v_mfma_f32_16x16x32_bf16 v[62:65], v[134:137], v[166:169], v[62:65]
	v_mfma_f32_16x16x32_bf16 v[58:61], v[142:145], v[166:169], v[58:61]
	v_mfma_f32_16x16x32_bf16 v[46:49], v[134:137], v[174:177], v[46:49]
	v_mfma_f32_16x16x32_bf16 v[42:45], v[142:145], v[174:177], v[42:45]
	v_mfma_f32_16x16x32_bf16 v[30:33], v[134:137], v[182:185], v[30:33]
	v_mfma_f32_16x16x32_bf16 v[26:29], v[142:145], v[182:185], v[26:29]
	v_mfma_f32_16x16x32_bf16 v[14:17], v[134:137], v[190:193], v[14:17]
	v_mfma_f32_16x16x32_bf16 v[10:13], v[142:145], v[190:193], v[10:13]
	v_mfma_f32_16x16x32_bf16 v[62:65], v[138:141], v[170:173], v[62:65]
	v_mfma_f32_16x16x32_bf16 v[58:61], v[146:149], v[170:173], v[58:61]
	v_mfma_f32_16x16x32_bf16 v[46:49], v[138:141], v[178:181], v[46:49]
	v_mfma_f32_16x16x32_bf16 v[42:45], v[146:149], v[178:181], v[42:45]
	v_mfma_f32_16x16x32_bf16 v[30:33], v[138:141], v[186:189], v[30:33]
	v_mfma_f32_16x16x32_bf16 v[26:29], v[146:149], v[186:189], v[26:29]
	v_mfma_f32_16x16x32_bf16 v[14:17], v[138:141], v[210:213], v[14:17]
	v_mfma_f32_16x16x32_bf16 v[10:13], v[146:149], v[210:213], v[10:13]
	s_setprio 0
	s_setprio 1
	v_mfma_f32_16x16x32_bf16 v[54:57], v[150:153], v[166:169], v[54:57]
	v_mfma_f32_16x16x32_bf16 v[50:53], v[158:161], v[166:169], v[50:53]
	v_mfma_f32_16x16x32_bf16 v[38:41], v[150:153], v[174:177], v[38:41]
	v_mfma_f32_16x16x32_bf16 v[34:37], v[158:161], v[174:177], v[34:37]
	v_mfma_f32_16x16x32_bf16 v[22:25], v[150:153], v[182:185], v[22:25]
	v_mfma_f32_16x16x32_bf16 v[18:21], v[158:161], v[182:185], v[18:21]
	v_mfma_f32_16x16x32_bf16 v[6:9], v[150:153], v[190:193], v[6:9]
	v_mfma_f32_16x16x32_bf16 v[2:5], v[158:161], v[190:193], v[2:5]
	v_mfma_f32_16x16x32_bf16 v[54:57], v[154:157], v[170:173], v[54:57]
	v_mfma_f32_16x16x32_bf16 v[50:53], v[162:165], v[170:173], v[50:53]
	v_mfma_f32_16x16x32_bf16 v[38:41], v[154:157], v[178:181], v[38:41]
	v_mfma_f32_16x16x32_bf16 v[34:37], v[162:165], v[178:181], v[34:37]
	v_mfma_f32_16x16x32_bf16 v[22:25], v[154:157], v[186:189], v[22:25]
	v_mfma_f32_16x16x32_bf16 v[18:21], v[162:165], v[186:189], v[18:21]
	v_mfma_f32_16x16x32_bf16 v[6:9], v[154:157], v[210:213], v[6:9]
	v_mfma_f32_16x16x32_bf16 v[2:5], v[162:165], v[210:213], v[2:5]
	s_setprio 0
	s_barrier
	s_add_u32 vcc_lo, vcc_lo, 0x100
	s_addc_u32 vcc_hi, vcc_hi, 0
	s_add_u32 s2, s2, 0x100
	s_addc_u32 s72, s72, 0
	s_cmp_ge_i32 s24, s68
	s_mov_b32 s8, s24
	s_cbranch_scc0 .LBB0_263
	s_mov_b32 s92, s3
	s_movk_i32 s93, 0x3fff
	s_movk_i32 s3, 0x2000
	s_and_b64 vcc, exec, s[44:45]
	s_cbranch_vccz .LBB0_266

; #define PG8_LDA(dst, b, h) do { _Pragma("unroll") for (int m = 0; m < 4; ++m) _Pragma("unroll") for (int k = 0; k < 2; ++k) dst[m][k] = *(const LAS bf16x8*)(lds + PG8_SA(b, h) + aoff + m * 2048 + k * 1024); } while (0)
; #define PG8_LDB(dst, b, h) do { _Pragma("unroll") for (int n = 0; n < 2; ++n) _Pragma("unroll") for (int k = 0; k < 2; ++k) dst[n][k] = *(const LAS bf16x8*)(lds + PG8_SB(b, h) + boff + n * 2048 + k * 1024); } while (0)
; #define PG8_BAR __builtin_amdgcn_s_barrier()
; #define PG8_SCHED __builtin_amdgcn_sched_barrier(0)
; #define PG8_STA(bufoff, gbase, ld) PG8_STAGE(bufoff, gbase, RA0 * (unsigned)(ld) + CC0, RA1 * (unsigned)(ld) + CC1)
; __device__ __forceinline__ void gemm_phase(LAS unsigned char* lds, const Sched& S, const Epi& E) {
;     ...
;         if (!has_next) {
;             const char* a1 = cA + (size_t)(nt - 1) * kstep;
;             PG8_LDB(B0, 0, 0); PG8_LDB(B1, 0, 1); PG8_SCHED; PG8_LDA(At, 0, 0); PG8_STA(PG8_SA(1, 1), a1 + hA, lda);
;     ...
;         if (wr == 1) PG8_BAR;
.LBB0_274:
	v_readlane_b32 s26, v250, 42
	s_nop 0
	s_cmp_eq_u32 s26, 0
	s_cbranch_scc1 .Lmy_nostagger2
	s_barrier

; #define PG8_BAR __builtin_amdgcn_s_barrier()
; __device__ __forceinline__ void gemm_phase(LAS unsigned char* lds, const Sched& S, const Epi& E) {
;     ...
;         if (wr == 0) PG8_BAR;
;         epi_run(E, acc, cur, wr, wc, fr, fq);
;         if (!has_next) break;
; #pragma unroll
;         for (int a = 0; a < 2; ++a)
; #pragma unroll
;             for (int b = 0; b < 2; ++b)
; #pragma unroll
;                 for (int m = 0; m < 4; ++m)
; #pragma unroll
;                     for (int n = 0; n < 2; ++n) acc[a][b][m][n] = (f32x4){0.f, 0.f, 0.f, 0.f};
;         cur = nxt; cA = nA; cB = nB; lda = nlda; ldb = nldb; ++ui;
;         if (wr == 1) PG8_BAR;
.LBB0_351:
	s_andn2_b64 vcc, exec, s[42:43]
	s_mov_b64 s[8:9], -1
	s_cbranch_vccnz .LBB0_258
	v_readlane_b32 s8, v250, 25
	v_readlane_b32 s9, v250, 26
	s_andn2_b64 vcc, exec, s[8:9]
	s_cbranch_vccnz .LBB0_257
	s_mov_b32 s8, 1
	s_nop 0
	v_writelane_b32 v250, s8, 42
	s_branch .LBB0_257
